# v12 + la_job: next chunk's decay-row prefetch issued right after B3 (beside q/v prefetch) instead of after the intra stage (registers free there)
# speedup vs baseline: 1.0042x; 1.0042x over previous
.LBB0_835:
	s_andn2_b64 vcc, exec, s[0:1]
	s_cbranch_vccnz .Lhg_gdone
	s_mov_b32 s5, s8
	s_ashr_i32 s1, s5, 31
	s_add_u32 s0, s5, s72
	s_addc_u32 s1, s1, s74
	s_sub_i32 s5, s4, s5
	s_min_i32 s5, s5, 64
	v_mov_b32_e32 v120, 0
	s_cmp_ge_i32 s75, s5
	v_mov_b32_e32 v91, 0
	s_cbranch_scc0 .LBB0_881
	s_cmp_ge_i32 s76, s5
	s_cbranch_scc0 .LBB0_882

.LBB0_872:
	s_add_u32 s0, s0, s90
	s_addc_u32 s1, s1, s91
	s_lshl_b64 s[0:1], s[0:1], 13
	v_lshl_add_u64 v[176:177], v[92:93], 0, s[0:1]
	global_load_dword v176, v[176:177], off
.Lhg_gdone:
	ds_read_b64_tr_b16 v[62:63], v159 offset:53248
	ds_read_b64_tr_b16 v[64:65], v159 offset:54336
	ds_read_b64_tr_b16 v[58:59], v159 offset:61952
	ds_read_b64_tr_b16 v[60:61], v159 offset:63040
	v_mov_b32_e32 v66, 0
	s_andn2_b64 vcc, exec, s[14:15]
	v_mov_b32_e32 v68, 0
	v_mov_b32_e32 v69, 0
	v_mov_b32_e32 v70, 0
	v_mov_b32_e32 v71, 0
	s_cbranch_vccnz .LBB0_837
	ds_read_b128 v[184:187], v172
	ds_read_b128 v[188:191], v173
	ds_read_b128 v[192:195], v172 offset:64
	ds_read_b128 v[196:199], v173 offset:64
	ds_read_b128 v[200:203], v172 offset:128
	ds_read_b128 v[204:207], v173 offset:128
	s_waitcnt lgkmcnt(6)
	s_waitcnt lgkmcnt(4)
	v_mfma_f32_16x16x32_bf16 v[68:71], v[184:187], v[188:191], 0
	s_waitcnt lgkmcnt(2)
	v_mfma_f32_16x16x32_bf16 v[68:71], v[192:195], v[196:199], v[68:71]
	s_waitcnt lgkmcnt(0)
	v_mfma_f32_16x16x32_bf16 v[68:71], v[200:203], v[204:207], v[68:71]
	ds_read_b128 v[72:75], v172 offset:192
	ds_read_b128 v[76:79], v173 offset:192
	s_waitcnt lgkmcnt(0)
	v_mfma_f32_16x16x32_bf16 v[68:71], v[72:75], v[76:79], v[68:71]

.LBB0_855:
	s_or_b64 exec, exec, s[20:21]
.LBB0_873:
	ds_read_b128 v[184:187], v133
	ds_read_b128 v[188:191], v163
	ds_read_b128 v[192:195], v163 offset:64
	ds_read_b128 v[196:199], v148
	ds_read_b128 v[200:203], v163 offset:2304
	ds_read_b128 v[204:207], v163 offset:2368
	s_waitcnt lgkmcnt(6)
	s_waitcnt lgkmcnt(5)
	v_pk_mul_f32 v[4:5], v[4:5], v[186:187]
	ds_read_b128 v[208:211], v149
	v_pk_mul_f32 v[2:3], v[2:3], v[184:185]
	s_nop 0
	s_waitcnt lgkmcnt(5)
	v_mfma_f32_16x16x32_bf16 v[2:5], v[188:191], v[62:65], v[2:5]
	ds_read_b128 v[184:187], v163 offset:4608
	s_waitcnt lgkmcnt(5)
	v_mfma_f32_16x16x32_bf16 v[2:5], v[192:195], v[58:61], v[2:5]
	ds_read_b128 v[188:191], v163 offset:4672
	s_waitcnt lgkmcnt(5)
	v_pk_mul_f32 v[12:13], v[12:13], v[198:199]
	ds_read_b128 v[192:195], v150
	v_pk_mul_f32 v[10:11], v[10:11], v[196:197]
	s_nop 0
	s_waitcnt lgkmcnt(5)
	v_mfma_f32_16x16x32_bf16 v[10:13], v[200:203], v[62:65], v[10:13]
	ds_read_b128 v[196:199], v163 offset:6912
	s_waitcnt lgkmcnt(5)
	v_mfma_f32_16x16x32_bf16 v[10:13], v[204:207], v[58:61], v[10:13]
	ds_read_b128 v[200:203], v163 offset:6976
	s_waitcnt lgkmcnt(5)
	v_pk_mul_f32 v[8:9], v[8:9], v[210:211]
	ds_read_b128 v[204:207], v151
	v_pk_mul_f32 v[6:7], v[6:7], v[208:209]
	s_nop 0
	s_waitcnt lgkmcnt(5)
	v_mfma_f32_16x16x32_bf16 v[6:9], v[184:187], v[62:65], v[6:9]
	ds_read_b128 v[184:187], v163 offset:9216
	s_waitcnt lgkmcnt(5)
	v_mfma_f32_16x16x32_bf16 v[6:9], v[188:191], v[58:61], v[6:9]
	ds_read_b128 v[188:191], v163 offset:9280
	s_waitcnt lgkmcnt(5)
	v_pk_mul_f32 v[16:17], v[16:17], v[194:195]
	ds_read_b128 v[208:211], v152
	v_pk_mul_f32 v[14:15], v[14:15], v[192:193]
	s_nop 0
	s_waitcnt lgkmcnt(5)
	v_mfma_f32_16x16x32_bf16 v[14:17], v[196:199], v[62:65], v[14:17]
	ds_read_b128 v[192:195], v163 offset:11520
	s_waitcnt lgkmcnt(5)
	v_mfma_f32_16x16x32_bf16 v[14:17], v[200:203], v[58:61], v[14:17]
	ds_read_b128 v[196:199], v163 offset:11584
	s_waitcnt lgkmcnt(5)
	v_pk_mul_f32 v[20:21], v[20:21], v[206:207]
	ds_read_b128 v[200:203], v153
	v_pk_mul_f32 v[18:19], v[18:19], v[204:205]
	s_nop 0
	s_waitcnt lgkmcnt(5)
	v_mfma_f32_16x16x32_bf16 v[18:21], v[184:187], v[62:65], v[18:21]
	ds_read_b128 v[184:187], v163 offset:13824
	s_waitcnt lgkmcnt(5)
	v_mfma_f32_16x16x32_bf16 v[18:21], v[188:191], v[58:61], v[18:21]
	ds_read_b128 v[188:191], v163 offset:13888
	s_waitcnt lgkmcnt(5)
	v_pk_mul_f32 v[24:25], v[24:25], v[210:211]
	ds_read_b128 v[204:207], v154
	v_pk_mul_f32 v[22:23], v[22:23], v[208:209]
	s_nop 0
	s_waitcnt lgkmcnt(5)
	v_mfma_f32_16x16x32_bf16 v[22:25], v[192:195], v[62:65], v[22:25]
	s_waitcnt lgkmcnt(4)
	v_mfma_f32_16x16x32_bf16 v[22:25], v[196:199], v[58:61], v[22:25]
	s_waitcnt lgkmcnt(3)
	v_pk_mul_f32 v[28:29], v[28:29], v[202:203]
	v_pk_mul_f32 v[26:27], v[26:27], v[200:201]
	s_nop 0
	s_waitcnt lgkmcnt(2)
	v_mfma_f32_16x16x32_bf16 v[26:29], v[184:187], v[62:65], v[26:29]
	s_waitcnt lgkmcnt(1)
	v_mfma_f32_16x16x32_bf16 v[26:29], v[188:191], v[58:61], v[26:29]
	s_waitcnt lgkmcnt(0)
	v_pk_mul_f32 v[32:33], v[32:33], v[206:207]
	v_pk_mul_f32 v[30:31], v[30:31], v[204:205]
	ds_read_b128 v[178:181], v163 offset:16128
	s_waitcnt lgkmcnt(0)
	v_mfma_f32_16x16x32_bf16 v[30:33], v[178:181], v[62:65], v[30:33]
	ds_read_b128 v[62:65], v163 offset:16192
	s_waitcnt lgkmcnt(0)
	s_barrier
	v_mfma_f32_16x16x32_bf16 v[30:33], v[62:65], v[58:61], v[30:33]
	s_and_saveexec_b64 s[20:21], s[68:69]
	s_cbranch_execz .LBB0_875
	v_add_u32_e32 v1, 0, v142
	v_add_u32_e32 v1, 0x14400, v1
	ds_read_b128 v[58:61], v1
	ds_read_b128 v[62:65], v1 offset:16
	s_mov_b32 s0, 0xf800000
	s_waitcnt lgkmcnt(0)
	v_mov_b32_e32 v178, v58
	v_mov_b32_e32 v179, v62
	v_mov_b32_e32 v62, v59
	v_pk_add_f32 v[58:59], v[178:179], v[62:63]
	v_mov_b32_e32 v62, v60
	v_mov_b32_e32 v63, v64
	v_mov_b32_e32 v64, v61
	v_pk_add_f32 v[60:61], v[62:63], v[64:65]
	s_waitcnt vmcnt(0)
	v_lshlrev_b32_e32 v62, 16, v37
	v_pk_add_f32 v[58:59], v[58:59], v[60:61]
	v_and_b32_e32 v63, 0xffff0000, v37
	v_add_f32_e32 v1, v58, v59
	v_fmamk_f32 v1, v1, 0x3c000000, v222
	v_cmp_gt_f32_e32 vcc, s0, v1
	v_mul_f32_e32 v35, 0x4f800000, v1
	s_nop 0
	v_cndmask_b32_e32 v1, v1, v35, vcc
	v_sqrt_f32_e32 v35, v1
	s_nop 0
	v_add_u32_e32 v58, -1, v35
	v_fma_f32 v59, -v58, v35, v1
	v_cmp_ge_f32_e64 s[0:1], 0, v59
	v_add_u32_e32 v59, 1, v35
	s_nop 0
	v_cndmask_b32_e64 v58, v35, v58, s[0:1]
	v_fma_f32 v35, -v59, v35, v1
	v_cmp_lt_f32_e64 s[0:1], 0, v35
	s_nop 1
	v_cndmask_b32_e64 v35, v58, v59, s[0:1]
	v_mul_f32_e32 v58, 0x37800000, v35
	v_cndmask_b32_e32 v35, v35, v58, vcc
	v_cmp_class_f32_e32 vcc, v1, v223
	s_nop 1
	v_cndmask_b32_e32 v1, v35, v1, vcc
	v_div_scale_f32 v35, s[0:1], v1, v1, 1.0
	v_rcp_f32_e32 v58, v35
	s_movk_i32 s0, 0x3000
	v_fma_f32 v59, -v35, v58, 1.0
	v_fmac_f32_e32 v58, v59, v58
	v_div_scale_f32 v59, vcc, 1.0, v1, 1.0
	v_mul_f32_e32 v60, v59, v58
	v_fma_f32 v61, -v35, v60, v59
	v_fmac_f32_e32 v60, v61, v58
	v_fma_f32 v35, -v35, v60, v59
	v_div_fmas_f32 v35, v35, v58, v60
	v_div_fixup_f32 v58, v35, v1, 1.0
	v_pk_mul_f32 v[60:61], v[80:81], v[58:59] op_sel_hi:[1,0]
	v_pk_mul_f32 v[58:59], v[78:79], v[58:59] op_sel_hi:[1,0]
	v_pk_mul_f32 v[60:61], v[40:41], v[60:61]
	v_pk_mul_f32 v[58:59], v[38:39], v[58:59]
	v_pk_mul_f32 v[60:61], v[60:61], v[62:63]
	s_nop 0
	v_cvt_pk_bf16_f32 v37, v60, v61
	v_lshlrev_b32_e32 v60, 16, v36
	v_and_b32_e32 v61, 0xffff0000, v36
	v_pk_mul_f32 v[58:59], v[58:59], v[60:61]
	s_nop 0
	v_cvt_pk_bf16_f32 v36, v58, v59
	v_mad_u64_u32 v[58:59], s[0:1], v116, s0, v[100:101]
	v_mad_i32_i24 v59, s19, v230, v59
	global_store_dwordx2 v[58:59], v[36:37], off
